# scan chunk end: sixteen per-step y stores from 8 lanes replaced by two all-lane stores (lane kq writes steps 2kq, 2kq+1), on top of earlier LDS reads
# speedup vs baseline: 1.0008x; 1.0008x over previous
.LBB0_1124:
	s_add_i32 s11, s12, s83
	s_add_i32 s14, s12, s2
	s_cmp_lg_u32 s12, 0
	s_cselect_b64 s[8:9], -1, 0
	s_and_b64 s[12:13], s[8:9], exec
	s_cselect_b32 s14, s14, s82
	s_or_b64 s[8:9], s[20:21], s[8:9]
	s_and_b64 s[12:13], s[20:21], exec
	s_cselect_b32 s11, s11, s14
	s_and_b64 s[12:13], s[8:9], exec
	s_cselect_b32 s12, s84, 0x400
	s_lshl_b32 s10, s10, 4
	s_or_b32 s10, s10, s95
	s_xor_b32 s17, s10, -4
	s_and_b32 s13, s11, 1
	s_or_b32 s14, s10, 2
	s_xor_b32 s15, s10, -3
	s_or_b32 s16, s10, 3
	s_add_i32 s17, s17, s12
	s_cmp_eq_u32 s13, 0
	s_cselect_b32 s16, s16, s17
	s_add_i32 s15, s15, s12
	s_cmp_eq_u32 s13, 0
	s_cselect_b32 s14, s14, s15
	s_xor_b32 s17, s10, -2
	s_or_b32 s15, s10, 1
	s_add_i32 s17, s17, s12
	s_cmp_eq_u32 s13, 0
	s_cselect_b32 s15, s15, s17
	s_not_b32 s17, s10
	s_add_i32 s12, s12, s17
	s_cmp_eq_u32 s13, 0
	s_cselect_b32 s10, s10, s12
	s_ashr_i32 s12, s11, 6
	s_lshl_b32 s17, s12, 10
	s_addk_i32 s17, 0x2000
	s_lshl_b32 s12, s12, 8
	s_and_b64 s[8:9], s[8:9], exec
	v_lshrrev_b32_e32 v2, s36, v168
	s_cselect_b32 s12, s12, s17
	s_lshl_b32 s8, s11, 5
	v_mul_lo_u32 v2, s60, v2
	s_and_b32 s8, s8, 0x7c0
	v_bfe_u32 v3, v168, 0, s36
	v_lshlrev_b32_e32 v2, 5, v2
	v_or_b32_e32 v8, s8, v168
	v_readlane_b32 s64, v237, 2
	v_lshl_add_u32 v70, v3, 4, v2
	v_lshlrev_b32_e32 v2, 2, v8
	v_readlane_b32 s65, v237, 3
	s_lshl_b32 s34, s8, 1
	v_readlane_b32 s66, v237, 4
	v_readlane_b32 s67, v237, 5
	v_readlane_b32 s68, v237, 6
	v_readlane_b32 s69, v237, 7
	global_load_dword v102, v2, s[64:65]
	s_nop 1
	global_load_dword v101, v2, s[66:67]
	s_nop 0
	global_load_dword v100, v2, s[68:69]
	v_lshl_add_u64 v[2:3], v[76:77], 0, s[34:35]
	s_add_i32 s10, s12, s10
	s_mulk_i32 s13, 0x3000
	s_ashr_i32 s11, s10, 31
	ds_read_b128 v[138:141], v83 offset:12288
	ds_read_b128 v[26:29], v83 offset:12304
	v_mad_i64_i32 v[4:5], s[8:9], s10, v73, v[2:3]
	s_add_u32 s8, s10, s13
	global_load_ushort v109, v[4:5], off
	v_add_co_u32_e32 v4, vcc, s43, v4
	ds_read_b128 v[10:13], v83 offset:12544
	ds_read_b128 v[14:17], v83 offset:12560
	s_addc_u32 s9, s11, 0
	s_nop 0
	v_addc_co_u32_e32 v5, vcc, 0, v5, vcc
	s_lshl_b64 s[8:9], s[8:9], 11
	ds_read_b128 v[18:21], v83 offset:12800
	ds_read_b128 v[22:25], v83 offset:12816
	global_load_ushort v123, v[4:5], off offset:-4096
	global_load_ushort v124, v[4:5], off
	v_mov_b32_e32 v5, s9
	v_or_b32_e32 v4, s8, v8
	v_lshl_add_u64 v[6:7], s[22:23], 0, v[4:5]
	v_lshl_add_u64 v[4:5], s[24:25], 0, v[4:5]
	s_add_i32 s10, s12, s15
	global_load_ubyte v115, v[6:7], off
	global_load_ubyte v116, v[4:5], off
	s_ashr_i32 s11, s10, 31
	v_mad_i64_i32 v[4:5], s[8:9], s10, v73, v[2:3]
	s_add_u32 s8, s10, s13
	global_load_ushort v105, v[4:5], off
	v_add_co_u32_e32 v4, vcc, s43, v4
	s_addc_u32 s9, s11, 0
	s_nop 0
	v_addc_co_u32_e32 v5, vcc, 0, v5, vcc
	s_lshl_b64 s[8:9], s[8:9], 11
	global_load_ushort v117, v[4:5], off offset:-4096
	global_load_ushort v118, v[4:5], off
	v_mov_b32_e32 v5, s9
	ds_read_b128 v[142:145], v83 offset:13056
	ds_read_b128 v[30:33], v83 offset:13072
	v_or_b32_e32 v4, s8, v8
	v_lshl_add_u64 v[6:7], s[22:23], 0, v[4:5]
	v_lshl_add_u64 v[4:5], s[24:25], 0, v[4:5]
	s_add_i32 s10, s12, s14
	global_load_ubyte v113, v[6:7], off
	ds_read_b128 v[34:37], v83 offset:13312
	ds_read_b128 v[38:41], v83 offset:13328
	global_load_ubyte v114, v[4:5], off
	s_ashr_i32 s11, s10, 31
	v_mad_i64_i32 v[4:5], s[8:9], s10, v73, v[2:3]
	s_add_u32 s8, s10, s13
	global_load_ushort v104, v[4:5], off
	v_add_co_u32_e32 v4, vcc, s43, v4
	ds_read_b64 v[136:137], v82 offset:13568
	s_addc_u32 s9, s11, 0
	s_nop 0
	v_addc_co_u32_e32 v5, vcc, 0, v5, vcc
	s_lshl_b64 s[8:9], s[8:9], 11
	s_add_i32 s12, s12, s16
	global_load_ushort v106, v[4:5], off offset:-4096
	global_load_ushort v107, v[4:5], off
	v_mov_b32_e32 v5, s9
	v_or_b32_e32 v4, s8, v8
	s_ashr_i32 s10, s12, 31
	v_mad_i64_i32 v[2:3], s[8:9], s12, v73, v[2:3]
	v_lshl_add_u64 v[6:7], s[22:23], 0, v[4:5]
	v_lshl_add_u64 v[4:5], s[24:25], 0, v[4:5]
	s_add_u32 s8, s12, s13
	global_load_ubyte v112, v[6:7], off
	global_load_ubyte v122, v[4:5], off
	global_load_ushort v110, v[2:3], off
	v_add_co_u32_e32 v2, vcc, s43, v2
	s_addc_u32 s9, s10, 0
	s_nop 0
	v_addc_co_u32_e32 v3, vcc, 0, v3, vcc
	s_lshl_b64 s[8:9], s[8:9], 11
	global_load_ushort v108, v[2:3], off offset:-4096
	global_load_ushort v111, v[2:3], off
	v_mov_b32_e32 v3, s9
	v_or_b32_e32 v2, s8, v8
	v_lshl_add_u64 v[4:5], s[22:23], 0, v[2:3]
	v_lshl_add_u64 v[2:3], s[24:25], 0, v[2:3]
	global_load_ubyte v119, v[4:5], off
	global_load_ubyte v120, v[2:3], off
	s_nop 0
	s_waitcnt lgkmcnt(10)
	v_mul_f32_e32 v65, v42, v138
	v_mul_f32_e32 v138, v52, v138
	v_fmac_f32_e32 v65, v43, v139
	v_fmac_f32_e32 v138, v53, v139
	v_fmac_f32_e32 v65, v44, v140
	v_fmac_f32_e32 v138, v54, v140
	v_fmac_f32_e32 v65, v45, v141
	v_fmac_f32_e32 v138, v55, v141
	s_waitcnt lgkmcnt(9)
	v_fmac_f32_e32 v65, v48, v26
	v_fmac_f32_e32 v138, v56, v26
	v_fmac_f32_e32 v65, v49, v27
	v_fmac_f32_e32 v138, v57, v27
	v_fmac_f32_e32 v65, v50, v28
	v_fmac_f32_e32 v138, v58, v28
	v_fmac_f32_e32 v65, v51, v29
	v_fmac_f32_e32 v138, v59, v29
	s_nop 1
	v_add_f32_dpp v65, v65, v65 quad_perm:[1,0,3,2] row_mask:0xf bank_mask:0xf bound_ctrl:1
	v_add_f32_dpp v138, v138, v138 quad_perm:[1,0,3,2] row_mask:0xf bank_mask:0xf bound_ctrl:1
	s_nop 0
	v_add_f32_dpp v65, v65, v65 quad_perm:[2,3,0,1] row_mask:0xf bank_mask:0xf bound_ctrl:1
	v_add_f32_dpp v138, v138, v138 quad_perm:[2,3,0,1] row_mask:0xf bank_mask:0xf bound_ctrl:1
	s_nop 0
	v_add_f32_dpp v65, v65, v65 row_half_mirror row_mask:0xf bank_mask:0xf bound_ctrl:1
	ds_read_b128 v[146:149], v83 offset:13824
	ds_read_b128 v[26:29], v83 offset:13840
	v_add_f32_dpp v138, v138, v138 row_half_mirror row_mask:0xf bank_mask:0xf bound_ctrl:1
	s_waitcnt lgkmcnt(7)
	v_mul_f32_e32 v64, v22, v65
	v_fmac_f32_e32 v64, v48, v14
	v_mul_f32_e32 v48, v23, v65
	v_fmac_f32_e32 v48, v49, v15
	ds_read_b128 v[150:153], v83 offset:14080
	ds_read_b128 v[6:9], v83 offset:14096
	v_mul_f32_e32 v49, v24, v65
	v_fmac_f32_e32 v49, v50, v16
	v_mul_f32_e32 v50, v25, v65
	s_nop 0
	v_fmac_f32_e32 v50, v51, v17
	v_mul_f32_e32 v60, v18, v65
	ds_read_b128 v[154:157], v83 offset:14336
	ds_read_b128 v[158:161], v83 offset:14352
	v_mul_f32_e32 v51, v18, v138
	v_fmac_f32_e32 v60, v42, v10
	v_mul_f32_e32 v61, v19, v65
	v_mul_f32_e32 v62, v20, v65
	v_mul_f32_e32 v63, v21, v65
	v_fmac_f32_e32 v51, v52, v10
	v_mul_f32_e32 v65, v19, v138
	v_fmac_f32_e32 v61, v43, v11
	s_waitcnt lgkmcnt(6)
	v_fmac_f32_e32 v60, v136, v142
	v_fmac_f32_e32 v62, v44, v12
	v_fmac_f32_e32 v63, v45, v13
	v_fmac_f32_e32 v51, v137, v142
	v_fmac_f32_e32 v65, v53, v11
	v_mul_f32_e32 v66, v20, v138
	s_nop 0
	v_fmac_f32_e32 v61, v136, v143
	v_fmac_f32_e32 v62, v136, v144
	v_fmac_f32_e32 v63, v136, v145
	v_fmac_f32_e32 v64, v136, v30
	v_fmac_f32_e32 v48, v136, v31
	v_fmac_f32_e32 v49, v136, v32
	v_fmac_f32_e32 v50, v136, v33
	v_mul_f32_e32 v135, v34, v60
	v_fmac_f32_e32 v65, v137, v143
	v_fmac_f32_e32 v66, v54, v12
	v_mul_f32_e32 v67, v21, v138
	v_mul_f32_e32 v136, v34, v51
	v_fmac_f32_e32 v66, v137, v144
	v_fmac_f32_e32 v135, v61, v35
	v_fmac_f32_e32 v67, v55, v13
	v_mul_f32_e32 v68, v22, v138
	v_fmac_f32_e32 v136, v65, v35
	v_fmac_f32_e32 v67, v137, v145
	v_fmac_f32_e32 v135, v62, v36
	v_fmac_f32_e32 v68, v56, v14
	v_mul_f32_e32 v69, v23, v138
	v_fmac_f32_e32 v136, v66, v36
	ds_read_b128 v[10:13], v83 offset:14592
	ds_read_b128 v[18:21], v83 offset:14608
	ds_read_b128 v[162:165], v83 offset:14848
	ds_read_b128 v[178:181], v83 offset:14864
	ds_read_b64 v[22:23], v82 offset:15104
	v_fmac_f32_e32 v68, v137, v30
	v_fmac_f32_e32 v135, v63, v37
	v_fmac_f32_e32 v69, v57, v15
	v_mul_f32_e32 v80, v24, v138
	v_fmac_f32_e32 v136, v67, v37
	v_fmac_f32_e32 v69, v137, v31
	v_fmac_f32_e32 v135, v64, v38
	v_fmac_f32_e32 v80, v58, v16
	v_mul_f32_e32 v81, v25, v138
	v_fmac_f32_e32 v136, v68, v38
	v_fmac_f32_e32 v80, v137, v32
	v_fmac_f32_e32 v135, v48, v39
	v_fmac_f32_e32 v81, v59, v17
	ds_read_b128 v[188:191], v83 offset:15360
	ds_read_b128 v[42:45], v83 offset:15376
	v_fmac_f32_e32 v136, v69, v39
	v_fmac_f32_e32 v81, v137, v33
	v_fmac_f32_e32 v135, v49, v40
	v_fmac_f32_e32 v136, v80, v40
	global_load_dwordx4 v[2:5], v70, s[38:39]
	v_fmac_f32_e32 v135, v50, v41
	v_fmac_f32_e32 v136, v81, v41
	s_nop 0
	s_waitcnt lgkmcnt(12)
	v_mul_f32_e32 v59, v60, v146
	v_mul_f32_e32 v146, v51, v146
	v_fmac_f32_e32 v59, v61, v147
	v_fmac_f32_e32 v146, v65, v147
	v_fmac_f32_e32 v59, v62, v148
	v_fmac_f32_e32 v146, v66, v148
	v_fmac_f32_e32 v59, v63, v149
	v_fmac_f32_e32 v146, v67, v149
	s_waitcnt lgkmcnt(11)
	v_fmac_f32_e32 v59, v64, v26
	v_fmac_f32_e32 v146, v68, v26
	s_mov_b32 s61, s35
	v_fmac_f32_e32 v59, v48, v27
	v_fmac_f32_e32 v146, v69, v27
	v_fmac_f32_e32 v59, v49, v28
	v_fmac_f32_e32 v146, v80, v28
	v_fmac_f32_e32 v59, v50, v29
	v_fmac_f32_e32 v146, v81, v29
	s_nop 1
	v_add_f32_dpp v59, v59, v59 quad_perm:[1,0,3,2] row_mask:0xf bank_mask:0xf bound_ctrl:1
	v_add_f32_dpp v146, v146, v146 quad_perm:[1,0,3,2] row_mask:0xf bank_mask:0xf bound_ctrl:1
	s_nop 0
	v_add_f32_dpp v59, v59, v59 quad_perm:[2,3,0,1] row_mask:0xf bank_mask:0xf bound_ctrl:1
	v_add_f32_dpp v146, v146, v146 quad_perm:[2,3,0,1] row_mask:0xf bank_mask:0xf bound_ctrl:1
	ds_read_b128 v[194:197], v83 offset:15616
	ds_read_b128 v[202:205], v83 offset:15632
	ds_read_b128 v[34:37], v83 offset:15872
	ds_read_b128 v[14:17], v83 offset:15888
	s_nop 0
	v_add_f32_dpp v59, v59, v59 row_half_mirror row_mask:0xf bank_mask:0xf bound_ctrl:1
	v_add_f32_dpp v146, v146, v146 row_half_mirror row_mask:0xf bank_mask:0xf bound_ctrl:1
	v_lshl_add_u64 v[46:47], s[38:39], 0, v[70:71]
	s_waitcnt lgkmcnt(12)
	v_mul_f32_e32 v52, v154, v59
	v_fmac_f32_e32 v52, v60, v150
	v_mul_f32_e32 v53, v155, v59
	v_mul_f32_e32 v54, v156, v59
	v_mul_f32_e32 v55, v157, v59
	s_waitcnt lgkmcnt(11)
	v_mul_f32_e32 v56, v158, v59
	v_mul_f32_e32 v57, v159, v59
	v_mul_f32_e32 v58, v160, v59
	v_mul_f32_e32 v59, v161, v59
	v_mul_f32_e32 v60, v154, v146
	s_lshl_b64 s[8:9], s[60:61], 2
	v_fmac_f32_e32 v60, v51, v150
	v_fmac_f32_e32 v59, v50, v9
	v_mul_f32_e32 v142, v158, v146
	v_mul_f32_e32 v143, v159, v146
	v_mul_f32_e32 v144, v160, v146
	v_mul_f32_e32 v145, v161, v146
	v_lshl_add_u64 v[50:51], v[46:47], 0, s[8:9]
	v_fmac_f32_e32 v53, v61, v151
	v_fmac_f32_e32 v54, v62, v152
	v_fmac_f32_e32 v56, v64, v6
	v_fmac_f32_e32 v57, v48, v7
	v_fmac_f32_e32 v58, v49, v8
	v_mul_f32_e32 v61, v155, v146
	v_mul_f32_e32 v62, v156, v146
	v_mul_f32_e32 v140, v157, v146
	v_fmac_f32_e32 v142, v68, v6
	v_fmac_f32_e32 v143, v69, v7
	v_fmac_f32_e32 v144, v80, v8
	v_fmac_f32_e32 v145, v81, v9
	global_load_dwordx4 v[6:9], v[50:51], off
	v_fmac_f32_e32 v61, v65, v151
	s_waitcnt lgkmcnt(6)
	v_fmac_f32_e32 v52, v22, v10
	v_fmac_f32_e32 v60, v23, v10
	ds_read_b128 v[38:41], v83 offset:16128
	ds_read_b128 v[148:151], v83 offset:16144
	v_fmac_f32_e32 v62, v66, v152
	v_fmac_f32_e32 v53, v22, v11
	v_fmac_f32_e32 v55, v63, v153
	v_fmac_f32_e32 v61, v23, v11
	s_waitcnt lgkmcnt(7)
	v_mul_f32_e32 v63, v52, v188
	v_mul_f32_e32 v188, v60, v188
	v_fmac_f32_e32 v140, v67, v153
	v_fmac_f32_e32 v54, v22, v12
	v_fmac_f32_e32 v62, v23, v12
	s_nop 0
	v_fmac_f32_e32 v63, v53, v189
	v_fmac_f32_e32 v188, v61, v189
	v_fmac_f32_e32 v55, v22, v13
	v_fmac_f32_e32 v56, v22, v18
	v_fmac_f32_e32 v57, v22, v19
	ds_read_b128 v[30:33], v83 offset:16384
	ds_read_b128 v[26:29], v83 offset:16400
	ds_read_b64 v[146:147], v82 offset:16640
	v_fmac_f32_e32 v58, v22, v20
	v_fmac_f32_e32 v59, v22, v21
	v_mul_f32_e32 v137, v162, v52
	v_fmac_f32_e32 v140, v23, v13
	v_mul_f32_e32 v138, v162, v60
	v_fmac_f32_e32 v142, v23, v18
	v_fmac_f32_e32 v63, v54, v190
	v_fmac_f32_e32 v188, v62, v190
	v_fmac_f32_e32 v137, v53, v163
	v_fmac_f32_e32 v143, v23, v19
	v_fmac_f32_e32 v144, v23, v20
	ds_read_b128 v[154:157], v83 offset:16896
	ds_read_b128 v[46:49], v83 offset:16912
	v_fmac_f32_e32 v145, v23, v21
	v_fmac_f32_e32 v138, v61, v163
	v_fmac_f32_e32 v63, v55, v191
	v_fmac_f32_e32 v188, v140, v191
	v_fmac_f32_e32 v137, v54, v164
	v_fmac_f32_e32 v138, v62, v164
	s_waitcnt lgkmcnt(11)
	v_fmac_f32_e32 v63, v56, v42
	v_fmac_f32_e32 v188, v142, v42
	v_fmac_f32_e32 v137, v55, v165
	v_fmac_f32_e32 v138, v140, v165
	s_nop 0
	v_fmac_f32_e32 v63, v57, v43
	v_fmac_f32_e32 v188, v143, v43
	v_fmac_f32_e32 v137, v56, v178
	v_fmac_f32_e32 v138, v142, v178
	v_fmac_f32_e32 v63, v58, v44
	v_fmac_f32_e32 v188, v144, v44
	v_fmac_f32_e32 v137, v57, v179
	v_fmac_f32_e32 v138, v143, v179
	v_fmac_f32_e32 v63, v59, v45
	v_fmac_f32_e32 v188, v145, v45
	v_fmac_f32_e32 v137, v58, v180
	v_fmac_f32_e32 v138, v144, v180
	s_nop 1
	v_add_f32_dpp v63, v63, v63 quad_perm:[1,0,3,2] row_mask:0xf bank_mask:0xf bound_ctrl:1
	v_add_f32_dpp v188, v188, v188 quad_perm:[1,0,3,2] row_mask:0xf bank_mask:0xf bound_ctrl:1
	s_nop 0
	v_add_f32_dpp v63, v63, v63 quad_perm:[2,3,0,1] row_mask:0xf bank_mask:0xf bound_ctrl:1
	v_add_f32_dpp v188, v188, v188 quad_perm:[2,3,0,1] row_mask:0xf bank_mask:0xf bound_ctrl:1
	s_nop 0
	v_add_f32_dpp v63, v63, v63 row_half_mirror row_mask:0xf bank_mask:0xf bound_ctrl:1
	v_add_f32_dpp v188, v188, v188 row_half_mirror row_mask:0xf bank_mask:0xf bound_ctrl:1
	v_fmac_f32_e32 v137, v59, v181
	s_waitcnt lgkmcnt(8)
	v_mul_f32_e32 v80, v36, v63
	v_mul_f32_e32 v70, v37, v63
	s_waitcnt lgkmcnt(7)
	v_mul_f32_e32 v67, v16, v63
	v_mul_f32_e32 v66, v17, v63
	v_mul_f32_e32 v65, v34, v188
	v_mul_f32_e32 v64, v35, v188
	v_fmac_f32_e32 v138, v145, v181
	v_mul_f32_e32 v141, v34, v63
	ds_read_b128 v[158:161], v83 offset:17152
	ds_read_b128 v[162:165], v83 offset:17168
	ds_read_b128 v[178:181], v83 offset:17408
	ds_read_b128 v[22:25], v83 offset:17424
	v_mul_f32_e32 v81, v35, v63
	v_fmac_f32_e32 v80, v54, v196
	v_fmac_f32_e32 v70, v55, v197
	v_mul_f32_e32 v69, v14, v63
	v_mul_f32_e32 v68, v15, v63
	v_fmac_f32_e32 v67, v58, v204
	v_fmac_f32_e32 v66, v59, v205
	v_fmac_f32_e32 v65, v60, v194
	v_fmac_f32_e32 v64, v61, v195
	ds_read_b128 v[42:45], v83 offset:17664
	ds_read_b128 v[206:209], v83 offset:17680
	v_mul_f32_e32 v63, v36, v188
	v_mul_f32_e32 v61, v14, v188
	ds_read_b128 v[212:215], v83 offset:17920
	ds_read_b128 v[18:21], v83 offset:17936
	v_mul_f32_e32 v60, v15, v188
	v_mul_f32_e32 v59, v16, v188
	v_mul_f32_e32 v58, v17, v188
	v_lshl_add_u64 v[54:55], v[50:51], 0, s[8:9]
	v_fmac_f32_e32 v141, v52, v194
	v_fmac_f32_e32 v81, v53, v195
	v_fmac_f32_e32 v69, v56, v202
	v_fmac_f32_e32 v68, v57, v203
	v_fmac_f32_e32 v63, v62, v196
	v_mul_f32_e32 v62, v37, v188
	v_fmac_f32_e32 v61, v142, v202
	v_fmac_f32_e32 v60, v143, v203
	ds_read_b64 v[56:57], v82 offset:18176
	v_fmac_f32_e32 v59, v144, v204
	v_fmac_f32_e32 v58, v145, v205
	global_load_dwordx4 v[10:13], v[54:55], off
	v_fmac_f32_e32 v62, v140, v197
	s_waitcnt lgkmcnt(11)
	v_fmac_f32_e32 v141, v146, v38
	v_fmac_f32_e32 v65, v147, v38
	v_fmac_f32_e32 v81, v146, v39
	v_mul_f32_e32 v139, v30, v141
	v_fmac_f32_e32 v64, v147, v39
	v_mul_f32_e32 v140, v30, v65
	s_nop 0
	s_waitcnt lgkmcnt(10)
	v_mul_f32_e32 v142, v141, v154
	v_fmac_f32_e32 v80, v146, v40
	v_fmac_f32_e32 v139, v81, v31
	v_fmac_f32_e32 v63, v147, v40
	v_fmac_f32_e32 v140, v64, v31
	v_mul_f32_e32 v154, v65, v154
	v_fmac_f32_e32 v70, v146, v41
	v_fmac_f32_e32 v139, v80, v32
	v_fmac_f32_e32 v62, v147, v41
	v_fmac_f32_e32 v140, v63, v32
	s_nop 0
	v_fmac_f32_e32 v142, v81, v155
	v_fmac_f32_e32 v154, v64, v155
	v_fmac_f32_e32 v69, v146, v148
	v_fmac_f32_e32 v139, v70, v33
	v_fmac_f32_e32 v61, v147, v148
	v_fmac_f32_e32 v140, v62, v33
	v_fmac_f32_e32 v142, v80, v156
	v_fmac_f32_e32 v154, v63, v156
	s_nop 0
	v_fmac_f32_e32 v68, v146, v149
	v_fmac_f32_e32 v139, v69, v26
	v_fmac_f32_e32 v60, v147, v149
	v_fmac_f32_e32 v140, v61, v26
	v_fmac_f32_e32 v67, v146, v150
	v_fmac_f32_e32 v142, v70, v157
	v_fmac_f32_e32 v154, v62, v157
	v_fmac_f32_e32 v66, v146, v151
	v_fmac_f32_e32 v139, v68, v27
	v_fmac_f32_e32 v59, v147, v150
	v_fmac_f32_e32 v58, v147, v151
	v_fmac_f32_e32 v140, v60, v27
	s_waitcnt lgkmcnt(9)
	v_fmac_f32_e32 v142, v69, v46
	v_fmac_f32_e32 v154, v61, v46
	s_nop 0
	v_fmac_f32_e32 v139, v67, v28
	v_fmac_f32_e32 v140, v59, v28
	v_fmac_f32_e32 v142, v68, v47
	v_fmac_f32_e32 v154, v60, v47
	v_fmac_f32_e32 v139, v66, v29
	v_fmac_f32_e32 v140, v58, v29
	v_fmac_f32_e32 v142, v67, v48
	v_fmac_f32_e32 v154, v59, v48
	v_fmac_f32_e32 v142, v66, v49
	v_fmac_f32_e32 v154, v58, v49
	s_nop 1
	v_add_f32_dpp v142, v142, v142 quad_perm:[1,0,3,2] row_mask:0xf bank_mask:0xf bound_ctrl:1
	v_add_f32_dpp v154, v154, v154 quad_perm:[1,0,3,2] row_mask:0xf bank_mask:0xf bound_ctrl:1
	s_nop 0
	v_add_f32_dpp v142, v142, v142 quad_perm:[2,3,0,1] row_mask:0xf bank_mask:0xf bound_ctrl:1
	v_add_f32_dpp v154, v154, v154 quad_perm:[2,3,0,1] row_mask:0xf bank_mask:0xf bound_ctrl:1
	s_nop 0
	v_add_f32_dpp v142, v142, v142 row_half_mirror row_mask:0xf bank_mask:0xf bound_ctrl:1
	v_add_f32_dpp v154, v154, v154 row_half_mirror row_mask:0xf bank_mask:0xf bound_ctrl:1
	ds_read_b128 v[188:191], v83 offset:18432
	ds_read_b128 v[194:197], v83 offset:18448
	s_waitcnt lgkmcnt(8)
	v_mul_f32_e32 v143, v178, v142
	v_mul_f32_e32 v144, v179, v142
	v_mul_f32_e32 v148, v178, v154
	v_fmac_f32_e32 v143, v141, v158
	ds_read_b128 v[28:31], v83 offset:18688
	ds_read_b128 v[32:35], v83 offset:18704
	v_fmac_f32_e32 v144, v81, v159
	v_mul_f32_e32 v81, v180, v142
	v_fmac_f32_e32 v148, v65, v158
	v_mul_f32_e32 v149, v179, v154
	ds_read_b128 v[36:39], v83 offset:18944
	ds_read_b128 v[202:205], v83 offset:18960
	v_fmac_f32_e32 v149, v64, v159
	ds_read_b128 v[156:159], v83 offset:19200
	ds_read_b128 v[48:51], v83 offset:19216
	s_waitcnt lgkmcnt(8)
	v_fmac_f32_e32 v143, v56, v42
	v_fmac_f32_e32 v81, v80, v160
	v_mul_f32_e32 v80, v181, v142
	v_fmac_f32_e32 v148, v57, v42
	v_mul_f32_e32 v150, v180, v154
	s_nop 0
	v_fmac_f32_e32 v80, v70, v161
	v_fmac_f32_e32 v144, v56, v43
	v_mul_f32_e32 v70, v22, v142
	v_mul_f32_e32 v145, v23, v142
	ds_read_b128 v[220:223], v83 offset:19456
	v_mul_f32_e32 v146, v24, v142
	ds_read_b128 v[224:227], v83 offset:19472
	v_mul_f32_e32 v147, v25, v142
	v_mul_f32_e32 v141, v212, v143
	v_fmac_f32_e32 v149, v57, v43
	v_fmac_f32_e32 v150, v63, v160
	v_mul_f32_e32 v63, v181, v154
	v_mul_f32_e32 v142, v212, v148
	v_fmac_f32_e32 v63, v62, v161
	v_fmac_f32_e32 v81, v56, v44
	v_fmac_f32_e32 v141, v144, v213
	v_fmac_f32_e32 v150, v57, v44
	v_mul_f32_e32 v62, v22, v154
	v_fmac_f32_e32 v142, v149, v213
	v_mul_f32_e32 v151, v23, v154
	v_fmac_f32_e32 v80, v56, v45
	v_fmac_f32_e32 v70, v69, v162
	v_fmac_f32_e32 v141, v81, v214
	v_fmac_f32_e32 v63, v57, v45
	v_fmac_f32_e32 v62, v61, v162
	v_fmac_f32_e32 v142, v150, v214
	ds_read_b64 v[22:23], v82 offset:19712
	v_mul_f32_e32 v152, v24, v154
	v_fmac_f32_e32 v70, v56, v206
	v_fmac_f32_e32 v145, v68, v163
	v_fmac_f32_e32 v141, v80, v215
	v_fmac_f32_e32 v62, v57, v206
	v_fmac_f32_e32 v151, v60, v163
	v_fmac_f32_e32 v142, v63, v215
	v_mul_f32_e32 v153, v25, v154
	v_fmac_f32_e32 v145, v56, v207
	v_fmac_f32_e32 v146, v67, v164
	v_fmac_f32_e32 v141, v70, v18
	v_fmac_f32_e32 v151, v57, v207
	v_fmac_f32_e32 v152, v59, v164
	v_fmac_f32_e32 v142, v62, v18
	s_nop 0
	v_fmac_f32_e32 v147, v66, v165
	v_fmac_f32_e32 v146, v56, v208
	v_fmac_f32_e32 v141, v145, v19
	v_fmac_f32_e32 v152, v57, v208
	v_fmac_f32_e32 v153, v58, v165
	v_fmac_f32_e32 v142, v151, v19
	v_fmac_f32_e32 v147, v56, v209
	v_fmac_f32_e32 v141, v146, v20
	v_fmac_f32_e32 v153, v57, v209
	v_fmac_f32_e32 v142, v152, v20
	v_lshl_add_u64 v[18:19], v[54:55], 0, s[8:9]
	global_load_dwordx4 v[14:17], v[18:19], off
	v_fmac_f32_e32 v141, v147, v21
	v_fmac_f32_e32 v142, v153, v21
	s_nop 0
	s_waitcnt lgkmcnt(10)
	v_mul_f32_e32 v154, v143, v188
	v_mul_f32_e32 v188, v148, v188
	v_fmac_f32_e32 v154, v144, v189
	v_fmac_f32_e32 v188, v149, v189
	v_fmac_f32_e32 v154, v81, v190
	v_fmac_f32_e32 v188, v150, v190
	v_fmac_f32_e32 v154, v80, v191
	v_fmac_f32_e32 v188, v63, v191
	s_waitcnt lgkmcnt(9)
	v_fmac_f32_e32 v154, v70, v194
	v_fmac_f32_e32 v188, v62, v194
	v_fmac_f32_e32 v154, v145, v195
	v_fmac_f32_e32 v188, v151, v195
	v_fmac_f32_e32 v154, v146, v196
	v_fmac_f32_e32 v188, v152, v196
	v_fmac_f32_e32 v154, v147, v197
	v_fmac_f32_e32 v188, v153, v197
	s_nop 0
	s_nop 0
	s_nop 1
	v_add_f32_dpp v154, v154, v154 quad_perm:[1,0,3,2] row_mask:0xf bank_mask:0xf bound_ctrl:1
	v_add_f32_dpp v188, v188, v188 quad_perm:[1,0,3,2] row_mask:0xf bank_mask:0xf bound_ctrl:1
	s_nop 0
	v_add_f32_dpp v154, v154, v154 quad_perm:[2,3,0,1] row_mask:0xf bank_mask:0xf bound_ctrl:1
	v_add_f32_dpp v188, v188, v188 quad_perm:[2,3,0,1] row_mask:0xf bank_mask:0xf bound_ctrl:1
	s_nop 0
	v_add_f32_dpp v154, v154, v154 row_half_mirror row_mask:0xf bank_mask:0xf bound_ctrl:1
	v_add_f32_dpp v188, v188, v188 row_half_mirror row_mask:0xf bank_mask:0xf bound_ctrl:1
	ds_read_b128 v[58:61], v83 offset:19968
	ds_read_b128 v[54:57], v83 offset:19984
	s_nop 0
	s_waitcnt lgkmcnt(8)
	v_mul_f32_e32 v66, v38, v154
	s_waitcnt lgkmcnt(7)
	v_mul_f32_e32 v68, v202, v154
	v_mul_f32_e32 v64, v36, v154
	ds_read_b128 v[178:181], v83 offset:20224
	ds_read_b128 v[194:197], v83 offset:20240
	v_fmac_f32_e32 v66, v81, v30
	v_mul_f32_e32 v67, v39, v154
	v_fmac_f32_e32 v68, v70, v32
	v_mul_f32_e32 v70, v204, v154
	ds_read_b128 v[206:209], v83 offset:20480
	ds_read_b128 v[212:215], v83 offset:20496
	v_mul_f32_e32 v81, v36, v188
	v_fmac_f32_e32 v64, v143, v28
	v_mul_f32_e32 v65, v37, v154
	ds_read_b128 v[228:231], v83 offset:20736
	ds_read_b128 v[238:241], v83 offset:20752
	v_fmac_f32_e32 v67, v80, v31
	v_fmac_f32_e32 v70, v146, v34
	v_mul_f32_e32 v80, v205, v154
	v_fmac_f32_e32 v81, v148, v28
	v_mul_f32_e32 v146, v37, v188
	v_fmac_f32_e32 v65, v144, v29
	s_waitcnt lgkmcnt(8)
	v_fmac_f32_e32 v64, v22, v156
	v_fmac_f32_e32 v80, v147, v35
	v_fmac_f32_e32 v81, v23, v156
	v_fmac_f32_e32 v146, v149, v29
	v_mul_f32_e32 v147, v38, v188
	v_fmac_f32_e32 v65, v22, v157
	v_mul_f32_e32 v143, v220, v64
	v_fmac_f32_e32 v146, v23, v157
	v_fmac_f32_e32 v147, v150, v30
	v_mul_f32_e32 v148, v39, v188
	v_mul_f32_e32 v144, v220, v81
	v_fmac_f32_e32 v148, v63, v31
	v_fmac_f32_e32 v66, v22, v158
	v_fmac_f32_e32 v143, v65, v221
	ds_read_b128 v[42:45], v83 offset:20992
	ds_read_b128 v[38:41], v83 offset:21008
	ds_read_b64 v[160:161], v82 offset:21248
	v_fmac_f32_e32 v147, v23, v158
	v_mul_f32_e32 v149, v202, v188
	v_fmac_f32_e32 v144, v146, v221
	v_fmac_f32_e32 v149, v62, v32
	v_fmac_f32_e32 v67, v22, v159
	v_mul_f32_e32 v69, v203, v154
	v_fmac_f32_e32 v143, v66, v222
	v_fmac_f32_e32 v148, v23, v159
	v_mul_f32_e32 v150, v203, v188
	v_fmac_f32_e32 v144, v147, v222
	s_nop 0
	v_fmac_f32_e32 v69, v145, v33
	v_fmac_f32_e32 v68, v22, v48
	v_fmac_f32_e32 v143, v67, v223
	v_fmac_f32_e32 v149, v23, v48
	v_fmac_f32_e32 v150, v151, v33
	v_mul_f32_e32 v151, v204, v188
	v_fmac_f32_e32 v144, v148, v223
	v_fmac_f32_e32 v69, v22, v49
	v_fmac_f32_e32 v143, v68, v224
	v_fmac_f32_e32 v150, v23, v49
	v_fmac_f32_e32 v151, v152, v34
	v_mul_f32_e32 v152, v205, v188
	v_fmac_f32_e32 v144, v149, v224
	v_fmac_f32_e32 v152, v153, v35
	v_fmac_f32_e32 v70, v22, v50
	v_fmac_f32_e32 v143, v69, v225
	v_fmac_f32_e32 v151, v23, v50
	v_fmac_f32_e32 v144, v150, v225
	v_lshl_add_u64 v[62:63], v[18:19], 0, s[8:9]
	v_fmac_f32_e32 v80, v22, v51
	v_fmac_f32_e32 v143, v70, v226
	v_fmac_f32_e32 v152, v23, v51
	v_fmac_f32_e32 v144, v151, v226
	global_load_dwordx4 v[18:21], v[62:63], off
	v_fmac_f32_e32 v143, v80, v227
	v_fmac_f32_e32 v144, v152, v227
	s_nop 0
	ds_read_b128 v[188:191], v83 offset:21504
	ds_read_b128 v[46:49], v83 offset:21520
	s_waitcnt lgkmcnt(12)
	v_mul_f32_e32 v145, v64, v58
	v_mul_f32_e32 v58, v81, v58
	v_fmac_f32_e32 v145, v65, v59
	v_fmac_f32_e32 v58, v146, v59
	v_fmac_f32_e32 v145, v66, v60
	v_fmac_f32_e32 v58, v147, v60
	v_fmac_f32_e32 v145, v67, v61
	v_fmac_f32_e32 v58, v148, v61
	s_waitcnt lgkmcnt(11)
	v_fmac_f32_e32 v145, v68, v54
	v_fmac_f32_e32 v58, v149, v54
	v_fmac_f32_e32 v145, v69, v55
	v_fmac_f32_e32 v58, v150, v55
	v_fmac_f32_e32 v145, v70, v56
	v_fmac_f32_e32 v58, v151, v56
	v_fmac_f32_e32 v145, v80, v57
	v_fmac_f32_e32 v58, v152, v57
	s_nop 1
	v_add_f32_dpp v145, v145, v145 quad_perm:[1,0,3,2] row_mask:0xf bank_mask:0xf bound_ctrl:1
	v_add_f32_dpp v58, v58, v58 quad_perm:[1,0,3,2] row_mask:0xf bank_mask:0xf bound_ctrl:1
	s_nop 0
	v_add_f32_dpp v145, v145, v145 quad_perm:[2,3,0,1] row_mask:0xf bank_mask:0xf bound_ctrl:1
	v_add_f32_dpp v58, v58, v58 quad_perm:[2,3,0,1] row_mask:0xf bank_mask:0xf bound_ctrl:1
	s_nop 0
	v_add_f32_dpp v145, v145, v145 row_half_mirror row_mask:0xf bank_mask:0xf bound_ctrl:1
	v_add_f32_dpp v58, v58, v58 row_half_mirror row_mask:0xf bank_mask:0xf bound_ctrl:1
	s_nop 0
	ds_read_b128 v[34:37], v83 offset:21760
	ds_read_b128 v[26:29], v83 offset:21776
	ds_read_b128 v[50:53], v83 offset:22016
	ds_read_b128 v[30:33], v83 offset:22032
	s_waitcnt lgkmcnt(11)
	v_mul_f32_e32 v157, v212, v145
	v_fmac_f32_e32 v157, v68, v194
	v_mul_f32_e32 v68, v213, v145
	v_mul_f32_e32 v153, v206, v145
	v_mul_f32_e32 v154, v207, v145
	v_mul_f32_e32 v155, v208, v145
	v_mul_f32_e32 v156, v209, v145
	v_fmac_f32_e32 v68, v69, v195
	v_mul_f32_e32 v69, v214, v145
	v_mul_f32_e32 v158, v215, v145
	v_fmac_f32_e32 v153, v64, v178
	v_fmac_f32_e32 v154, v65, v179
	v_fmac_f32_e32 v155, v66, v180
	v_fmac_f32_e32 v156, v67, v181
	v_fmac_f32_e32 v69, v70, v196
	v_fmac_f32_e32 v158, v80, v197
	s_nop 0
	s_waitcnt lgkmcnt(6)
	v_fmac_f32_e32 v153, v160, v228
	ds_read_b128 v[54:57], v83 offset:22272
	v_fmac_f32_e32 v154, v160, v229
	ds_read_b128 v[202:205], v83 offset:22288
	v_fmac_f32_e32 v155, v160, v230
	v_fmac_f32_e32 v156, v160, v231
	v_fmac_f32_e32 v157, v160, v238
	v_fmac_f32_e32 v68, v160, v239
	v_fmac_f32_e32 v69, v160, v240
	v_fmac_f32_e32 v158, v160, v241
	v_mul_f32_e32 v160, v209, v58
	v_mul_f32_e32 v80, v206, v58
	v_fmac_f32_e32 v160, v148, v181
	v_mul_f32_e32 v148, v212, v58
	ds_read_b128 v[220:223], v83 offset:22528
	ds_read_b128 v[224:227], v83 offset:22544
	v_mul_f32_e32 v162, v213, v58
	v_mul_f32_e32 v163, v214, v58
	v_mul_f32_e32 v164, v215, v58
	v_lshl_add_u64 v[66:67], v[62:63], 0, s[8:9]
	v_fmac_f32_e32 v80, v81, v178
	v_mul_f32_e32 v81, v207, v58
	v_mul_f32_e32 v159, v208, v58
	v_fmac_f32_e32 v148, v149, v194
	v_fmac_f32_e32 v162, v150, v195
	v_fmac_f32_e32 v163, v151, v196
	v_fmac_f32_e32 v164, v152, v197
	ds_read_b64 v[166:167], v82 offset:22784
	global_load_dwordx4 v[22:25], v[66:67], off
	v_fmac_f32_e32 v81, v146, v179
	v_fmac_f32_e32 v80, v161, v228
	v_fmac_f32_e32 v81, v161, v229
	v_fmac_f32_e32 v159, v147, v180
	s_waitcnt lgkmcnt(10)
	v_mul_f32_e32 v147, v153, v188
	v_mul_f32_e32 v188, v80, v188
	v_fmac_f32_e32 v159, v161, v230
	v_mul_f32_e32 v145, v42, v153
	v_mul_f32_e32 v146, v42, v80
	v_fmac_f32_e32 v160, v161, v231
	v_fmac_f32_e32 v147, v154, v189
	v_fmac_f32_e32 v188, v81, v189
	v_fmac_f32_e32 v145, v154, v43
	v_fmac_f32_e32 v146, v81, v43
	v_fmac_f32_e32 v148, v161, v238
	v_fmac_f32_e32 v147, v155, v190
	v_fmac_f32_e32 v188, v159, v190
	v_fmac_f32_e32 v145, v155, v44
	v_fmac_f32_e32 v146, v159, v44
	v_fmac_f32_e32 v162, v161, v239
	v_fmac_f32_e32 v147, v156, v191
	v_fmac_f32_e32 v188, v160, v191
	v_fmac_f32_e32 v145, v156, v45
	v_fmac_f32_e32 v163, v161, v240
	v_fmac_f32_e32 v164, v161, v241
	v_fmac_f32_e32 v146, v160, v45
	s_waitcnt lgkmcnt(9)
	v_fmac_f32_e32 v147, v157, v46
	v_fmac_f32_e32 v188, v148, v46
	s_nop 0
	v_fmac_f32_e32 v145, v157, v38
	v_fmac_f32_e32 v146, v148, v38
	v_fmac_f32_e32 v147, v68, v47
	v_fmac_f32_e32 v188, v162, v47
	v_fmac_f32_e32 v145, v68, v39
	v_fmac_f32_e32 v146, v162, v39
	s_nop 0
	v_fmac_f32_e32 v147, v69, v48
	v_fmac_f32_e32 v188, v163, v48
	v_fmac_f32_e32 v145, v69, v40
	v_fmac_f32_e32 v146, v163, v40
	v_fmac_f32_e32 v147, v158, v49
	v_fmac_f32_e32 v188, v164, v49
	v_fmac_f32_e32 v145, v158, v41
	v_fmac_f32_e32 v146, v164, v41
	s_nop 0
	s_nop 1
	v_add_f32_dpp v147, v147, v147 quad_perm:[1,0,3,2] row_mask:0xf bank_mask:0xf bound_ctrl:1
	v_add_f32_dpp v188, v188, v188 quad_perm:[1,0,3,2] row_mask:0xf bank_mask:0xf bound_ctrl:1
	s_nop 0
	v_add_f32_dpp v147, v147, v147 quad_perm:[2,3,0,1] row_mask:0xf bank_mask:0xf bound_ctrl:1
	v_add_f32_dpp v188, v188, v188 quad_perm:[2,3,0,1] row_mask:0xf bank_mask:0xf bound_ctrl:1
	s_nop 0
	v_add_f32_dpp v147, v147, v147 row_half_mirror row_mask:0xf bank_mask:0xf bound_ctrl:1
	v_add_f32_dpp v188, v188, v188 row_half_mirror row_mask:0xf bank_mask:0xf bound_ctrl:1
	s_waitcnt lgkmcnt(6)
	v_mul_f32_e32 v150, v52, v147
	v_fmac_f32_e32 v150, v155, v36
	ds_read_b128 v[46:49], v83 offset:23040
	ds_read_b128 v[42:45], v83 offset:23056
	v_mul_f32_e32 v151, v53, v147
	s_waitcnt lgkmcnt(7)
	v_mul_f32_e32 v155, v33, v147
	s_nop 0
	v_fmac_f32_e32 v151, v156, v37
	ds_read_b128 v[178:181], v83 offset:23296
	ds_read_b128 v[194:197], v83 offset:23312
	v_mul_f32_e32 v70, v50, v147
	v_mul_f32_e32 v152, v30, v147
	ds_read_b128 v[38:41], v83 offset:23552
	v_fmac_f32_e32 v155, v158, v29
	v_mul_f32_e32 v156, v50, v188
	v_mul_f32_e32 v158, v52, v188
	v_fmac_f32_e32 v70, v153, v34
	v_mul_f32_e32 v149, v51, v147
	v_fmac_f32_e32 v152, v157, v26
	v_fmac_f32_e32 v156, v80, v34
	v_mul_f32_e32 v157, v51, v188
	v_fmac_f32_e32 v158, v159, v36
	v_mul_f32_e32 v159, v53, v188
	v_fmac_f32_e32 v159, v160, v37
	s_waitcnt lgkmcnt(5)
	v_fmac_f32_e32 v70, v166, v54
	v_fmac_f32_e32 v149, v154, v35
	v_fmac_f32_e32 v156, v167, v54
	v_fmac_f32_e32 v157, v81, v35
	ds_read_b128 v[34:37], v83 offset:23568
	v_mul_f32_e32 v160, v30, v188
	s_nop 0
	v_mul_f32_e32 v153, v31, v147
	v_fmac_f32_e32 v149, v166, v55
	v_mul_f32_e32 v154, v32, v147
	v_mul_f32_e32 v147, v220, v70
	ds_read_b128 v[206:209], v83 offset:23808
	ds_read_b128 v[212:215], v83 offset:23824
	v_fmac_f32_e32 v157, v167, v55
	v_fmac_f32_e32 v160, v148, v26
	v_mul_f32_e32 v148, v220, v156
	s_nop 0
	v_fmac_f32_e32 v150, v166, v56
	v_fmac_f32_e32 v147, v149, v221
	v_fmac_f32_e32 v158, v167, v56
	v_fmac_f32_e32 v148, v157, v221
	v_fmac_f32_e32 v151, v166, v57
	v_fmac_f32_e32 v147, v150, v222
	v_fmac_f32_e32 v159, v167, v57
	v_mul_f32_e32 v161, v31, v188
	v_fmac_f32_e32 v148, v158, v222
	ds_read_b128 v[62:65], v83 offset:24064
	ds_read_b128 v[58:61], v83 offset:24080
	s_nop 0
	v_fmac_f32_e32 v153, v68, v27
	v_fmac_f32_e32 v152, v166, v202
	v_fmac_f32_e32 v147, v151, v223
	v_fmac_f32_e32 v160, v167, v202
	ds_read_b64 v[52:53], v82 offset:24320
	v_fmac_f32_e32 v161, v162, v27
	v_mul_f32_e32 v162, v32, v188
	v_fmac_f32_e32 v148, v159, v223
	v_fmac_f32_e32 v154, v69, v28
	v_fmac_f32_e32 v153, v166, v203
	v_fmac_f32_e32 v147, v152, v224
	v_fmac_f32_e32 v161, v167, v203
	v_fmac_f32_e32 v162, v163, v28
	v_mul_f32_e32 v163, v33, v188
	v_fmac_f32_e32 v148, v160, v224
	v_fmac_f32_e32 v163, v164, v29
	v_fmac_f32_e32 v154, v166, v204
	v_fmac_f32_e32 v147, v153, v225
	v_fmac_f32_e32 v162, v167, v204
	v_fmac_f32_e32 v148, v161, v225
	v_lshl_add_u64 v[80:81], v[66:67], 0, s[8:9]
	v_fmac_f32_e32 v155, v166, v205
	v_fmac_f32_e32 v147, v154, v226
	v_fmac_f32_e32 v163, v167, v205
	v_fmac_f32_e32 v148, v162, v226
	global_load_dwordx4 v[26:29], v[80:81], off
	v_fmac_f32_e32 v147, v155, v227
	v_fmac_f32_e32 v148, v163, v227
	s_nop 0
	s_waitcnt lgkmcnt(10)
	v_mul_f32_e32 v164, v70, v46
	v_mul_f32_e32 v165, v156, v46
	v_fmac_f32_e32 v164, v149, v47
	v_fmac_f32_e32 v165, v157, v47
	v_fmac_f32_e32 v164, v150, v48
	v_fmac_f32_e32 v165, v158, v48
	v_fmac_f32_e32 v164, v151, v49
	v_fmac_f32_e32 v165, v159, v49
	s_waitcnt lgkmcnt(9)
	v_fmac_f32_e32 v164, v152, v42
	v_fmac_f32_e32 v165, v160, v42
	v_fmac_f32_e32 v164, v153, v43
	v_fmac_f32_e32 v165, v161, v43
	v_fmac_f32_e32 v164, v154, v44
	v_fmac_f32_e32 v165, v162, v44
	v_fmac_f32_e32 v164, v155, v45
	v_fmac_f32_e32 v165, v163, v45
	s_nop 1
	v_add_f32_dpp v164, v164, v164 quad_perm:[1,0,3,2] row_mask:0xf bank_mask:0xf bound_ctrl:1
	v_add_f32_dpp v165, v165, v165 quad_perm:[1,0,3,2] row_mask:0xf bank_mask:0xf bound_ctrl:1
	s_nop 0
	v_add_f32_dpp v164, v164, v164 quad_perm:[2,3,0,1] row_mask:0xf bank_mask:0xf bound_ctrl:1
	v_add_f32_dpp v165, v165, v165 quad_perm:[2,3,0,1] row_mask:0xf bank_mask:0xf bound_ctrl:1
	s_nop 0
	v_add_f32_dpp v164, v164, v164 row_half_mirror row_mask:0xf bank_mask:0xf bound_ctrl:1
	v_add_f32_dpp v165, v165, v165 row_half_mirror row_mask:0xf bank_mask:0xf bound_ctrl:1
	s_waitcnt lgkmcnt(5)
	v_mul_f32_e32 v42, v34, v164
	v_mul_f32_e32 v43, v35, v164
	v_mul_f32_e32 v34, v34, v165
	v_mul_f32_e32 v35, v35, v165
	v_fmac_f32_e32 v42, v152, v194
	v_fmac_f32_e32 v43, v153, v195
	v_mul_f32_e32 v44, v36, v164
	v_mul_f32_e32 v45, v37, v164
	v_fmac_f32_e32 v34, v160, v194
	v_fmac_f32_e32 v35, v161, v195
	v_mul_f32_e32 v36, v36, v165
	v_mul_f32_e32 v37, v37, v165
	v_lshl_add_u64 v[30:31], v[80:81], 0, s[8:9]
	v_fmac_f32_e32 v44, v154, v196
	v_fmac_f32_e32 v45, v155, v197
	v_fmac_f32_e32 v36, v162, v196
	v_fmac_f32_e32 v37, v163, v197
	global_load_dwordx4 v[30:33], v[30:31], off
	v_mul_f32_e32 v46, v38, v164
	v_mul_f32_e32 v38, v38, v165
	v_fmac_f32_e32 v46, v70, v178
	v_mul_f32_e32 v47, v39, v164
	v_mul_f32_e32 v48, v40, v164
	v_mul_f32_e32 v49, v41, v164
	v_fmac_f32_e32 v38, v156, v178
	v_mul_f32_e32 v39, v39, v165
	v_fmac_f32_e32 v47, v149, v179
	s_waitcnt lgkmcnt(0)
	v_fmac_f32_e32 v46, v52, v206
	v_fmac_f32_e32 v48, v150, v180
	v_fmac_f32_e32 v49, v151, v181
	v_fmac_f32_e32 v38, v53, v206
	v_fmac_f32_e32 v39, v157, v179
	v_mul_f32_e32 v40, v40, v165
	s_nop 0
	v_fmac_f32_e32 v47, v52, v207
	v_fmac_f32_e32 v48, v52, v208
	v_fmac_f32_e32 v49, v52, v209
	v_fmac_f32_e32 v42, v52, v212
	v_fmac_f32_e32 v43, v52, v213
	v_fmac_f32_e32 v44, v52, v214
	v_fmac_f32_e32 v45, v52, v215
	v_mul_f32_e32 v82, v62, v46
	v_fmac_f32_e32 v39, v53, v207
	v_fmac_f32_e32 v40, v158, v180
	v_mul_f32_e32 v41, v41, v165
	v_mul_f32_e32 v50, v62, v38
	v_fmac_f32_e32 v40, v53, v208
	v_fmac_f32_e32 v82, v47, v63
	v_fmac_f32_e32 v41, v159, v181
	v_fmac_f32_e32 v50, v39, v63
	v_fmac_f32_e32 v41, v53, v209
	v_fmac_f32_e32 v82, v48, v64
	v_fmac_f32_e32 v50, v40, v64
	v_fmac_f32_e32 v34, v53, v212
	v_fmac_f32_e32 v82, v49, v65
	v_fmac_f32_e32 v50, v41, v65
	v_fmac_f32_e32 v35, v53, v213
	v_fmac_f32_e32 v82, v42, v58
	v_fmac_f32_e32 v50, v34, v58
	v_fmac_f32_e32 v36, v53, v214
	v_fmac_f32_e32 v82, v43, v59
	v_fmac_f32_e32 v50, v35, v59
	v_fmac_f32_e32 v37, v53, v215
	v_fmac_f32_e32 v82, v44, v60
	v_fmac_f32_e32 v50, v36, v60
	v_readlane_b32 s70, v237, 8
	v_fmac_f32_e32 v82, v45, v61
	v_fmac_f32_e32 v50, v37, v61
	v_readlane_b32 s71, v237, 9
	v_readlane_b32 s72, v237, 10
	v_readlane_b32 s73, v237, 11
	v_readlane_b32 s74, v237, 12
	v_readlane_b32 s75, v237, 13
	v_readlane_b32 s76, v237, 14
	v_readlane_b32 s77, v237, 15
	v_readlane_b32 s78, v237, 16
	v_readlane_b32 s79, v237, 17
	s_nop 1
	v_add_f32_dpp v135, v135, v135 quad_perm:[1,0,3,2] row_mask:0xf bank_mask:0xf bound_ctrl:1
	v_add_f32_dpp v136, v136, v136 quad_perm:[1,0,3,2] row_mask:0xf bank_mask:0xf bound_ctrl:1
	s_nop 0
	v_add_f32_dpp v135, v135, v135 quad_perm:[2,3,0,1] row_mask:0xf bank_mask:0xf bound_ctrl:1
	v_add_f32_dpp v136, v136, v136 quad_perm:[2,3,0,1] row_mask:0xf bank_mask:0xf bound_ctrl:1
	s_nop 0
	v_add_f32_dpp v135, v135, v135 row_half_mirror row_mask:0xf bank_mask:0xf bound_ctrl:1
	v_add_f32_dpp v136, v136, v136 row_half_mirror row_mask:0xf bank_mask:0xf bound_ctrl:1
	s_nop 1
	v_add_f32_dpp v137, v137, v137 quad_perm:[1,0,3,2] row_mask:0xf bank_mask:0xf bound_ctrl:1
	v_add_f32_dpp v138, v138, v138 quad_perm:[1,0,3,2] row_mask:0xf bank_mask:0xf bound_ctrl:1
	s_nop 0
	v_add_f32_dpp v137, v137, v137 quad_perm:[2,3,0,1] row_mask:0xf bank_mask:0xf bound_ctrl:1
	v_add_f32_dpp v138, v138, v138 quad_perm:[2,3,0,1] row_mask:0xf bank_mask:0xf bound_ctrl:1
	s_nop 0
	v_add_f32_dpp v137, v137, v137 row_half_mirror row_mask:0xf bank_mask:0xf bound_ctrl:1
	v_add_f32_dpp v138, v138, v138 row_half_mirror row_mask:0xf bank_mask:0xf bound_ctrl:1
	s_nop 1
	v_add_f32_dpp v139, v139, v139 quad_perm:[1,0,3,2] row_mask:0xf bank_mask:0xf bound_ctrl:1
	v_add_f32_dpp v140, v140, v140 quad_perm:[1,0,3,2] row_mask:0xf bank_mask:0xf bound_ctrl:1
	s_nop 0
	v_add_f32_dpp v139, v139, v139 quad_perm:[2,3,0,1] row_mask:0xf bank_mask:0xf bound_ctrl:1
	v_add_f32_dpp v140, v140, v140 quad_perm:[2,3,0,1] row_mask:0xf bank_mask:0xf bound_ctrl:1
	s_nop 0
	v_add_f32_dpp v139, v139, v139 row_half_mirror row_mask:0xf bank_mask:0xf bound_ctrl:1
	v_add_f32_dpp v140, v140, v140 row_half_mirror row_mask:0xf bank_mask:0xf bound_ctrl:1
	s_nop 1
	v_add_f32_dpp v141, v141, v141 quad_perm:[1,0,3,2] row_mask:0xf bank_mask:0xf bound_ctrl:1
	v_add_f32_dpp v142, v142, v142 quad_perm:[1,0,3,2] row_mask:0xf bank_mask:0xf bound_ctrl:1
	s_nop 0
	v_add_f32_dpp v141, v141, v141 quad_perm:[2,3,0,1] row_mask:0xf bank_mask:0xf bound_ctrl:1
	v_add_f32_dpp v142, v142, v142 quad_perm:[2,3,0,1] row_mask:0xf bank_mask:0xf bound_ctrl:1
	s_nop 0
	v_add_f32_dpp v141, v141, v141 row_half_mirror row_mask:0xf bank_mask:0xf bound_ctrl:1
	v_add_f32_dpp v142, v142, v142 row_half_mirror row_mask:0xf bank_mask:0xf bound_ctrl:1
	s_nop 1
	v_add_f32_dpp v143, v143, v143 quad_perm:[1,0,3,2] row_mask:0xf bank_mask:0xf bound_ctrl:1
	v_add_f32_dpp v144, v144, v144 quad_perm:[1,0,3,2] row_mask:0xf bank_mask:0xf bound_ctrl:1
	s_nop 0
	v_add_f32_dpp v143, v143, v143 quad_perm:[2,3,0,1] row_mask:0xf bank_mask:0xf bound_ctrl:1
	v_add_f32_dpp v144, v144, v144 quad_perm:[2,3,0,1] row_mask:0xf bank_mask:0xf bound_ctrl:1
	s_nop 0
	v_add_f32_dpp v143, v143, v143 row_half_mirror row_mask:0xf bank_mask:0xf bound_ctrl:1
	v_add_f32_dpp v144, v144, v144 row_half_mirror row_mask:0xf bank_mask:0xf bound_ctrl:1
	s_nop 1
	v_add_f32_dpp v145, v145, v145 quad_perm:[1,0,3,2] row_mask:0xf bank_mask:0xf bound_ctrl:1
	v_add_f32_dpp v146, v146, v146 quad_perm:[1,0,3,2] row_mask:0xf bank_mask:0xf bound_ctrl:1
	s_nop 0
	v_add_f32_dpp v145, v145, v145 quad_perm:[2,3,0,1] row_mask:0xf bank_mask:0xf bound_ctrl:1
	v_add_f32_dpp v146, v146, v146 quad_perm:[2,3,0,1] row_mask:0xf bank_mask:0xf bound_ctrl:1
	s_nop 0
	v_add_f32_dpp v145, v145, v145 row_half_mirror row_mask:0xf bank_mask:0xf bound_ctrl:1
	v_add_f32_dpp v146, v146, v146 row_half_mirror row_mask:0xf bank_mask:0xf bound_ctrl:1
	s_nop 1
	v_add_f32_dpp v147, v147, v147 quad_perm:[1,0,3,2] row_mask:0xf bank_mask:0xf bound_ctrl:1
	v_add_f32_dpp v148, v148, v148 quad_perm:[1,0,3,2] row_mask:0xf bank_mask:0xf bound_ctrl:1
	s_nop 0
	v_add_f32_dpp v147, v147, v147 quad_perm:[2,3,0,1] row_mask:0xf bank_mask:0xf bound_ctrl:1
	v_add_f32_dpp v148, v148, v148 quad_perm:[2,3,0,1] row_mask:0xf bank_mask:0xf bound_ctrl:1
	s_nop 0
	v_add_f32_dpp v147, v147, v147 row_half_mirror row_mask:0xf bank_mask:0xf bound_ctrl:1
	v_add_f32_dpp v148, v148, v148 row_half_mirror row_mask:0xf bank_mask:0xf bound_ctrl:1
	s_nop 1
	v_add_f32_dpp v82, v82, v82 quad_perm:[1,0,3,2] row_mask:0xf bank_mask:0xf bound_ctrl:1
	v_add_f32_dpp v50, v50, v50 quad_perm:[1,0,3,2] row_mask:0xf bank_mask:0xf bound_ctrl:1
	s_nop 0
	v_add_f32_dpp v82, v82, v82 quad_perm:[2,3,0,1] row_mask:0xf bank_mask:0xf bound_ctrl:1
	v_add_f32_dpp v50, v50, v50 quad_perm:[2,3,0,1] row_mask:0xf bank_mask:0xf bound_ctrl:1
	s_nop 0
	v_add_f32_dpp v82, v82, v82 row_half_mirror row_mask:0xf bank_mask:0xf bound_ctrl:1
	v_add_f32_dpp v50, v50, v50 row_half_mirror row_mask:0xf bank_mask:0xf bound_ctrl:1
	v_cvt_pk_f16_f32 v54, v95, v96
	v_cvt_pk_f16_f32 v55, v98, v99
	v_cvt_pk_f16_f32 v56, v103, v121
	v_cvt_pk_f16_f32 v57, v125, v126
	v_cvt_pk_f16_f32 v58, v127, v128
	v_cvt_pk_f16_f32 v59, v129, v130
	v_cvt_pk_f16_f32 v60, v131, v132
	v_cvt_pk_f16_f32 v61, v133, v134
	v_cvt_pk_f16_f32 v69, v135, v136
	v_cvt_pk_f16_f32 v68, v137, v138
	v_cvt_pk_f16_f32 v67, v139, v140
	v_cvt_pk_f16_f32 v66, v141, v142
	v_cvt_pk_f16_f32 v65, v143, v144
	v_cvt_pk_f16_f32 v64, v145, v146
	v_cvt_pk_f16_f32 v63, v147, v148
	v_cvt_pk_f16_f32 v62, v82, v50
	v_and_b32_e32 v50, 1, v168
	v_and_b32_e32 v51, 7, v168
	v_cmp_ne_u32_e32 vcc, 0, v50
	s_and_b64 s[10:11], s[80:81], exec
	s_cselect_b32 s12, s84, 0x400
	s_lshl_b32 s13, s46, 4
	v_lshlrev_b32_e32 v51, 1, v51
	v_and_b32_e32 v50, 2, v168
	v_cndmask_b32_e32 v54, v54, v56, vcc
	v_cndmask_b32_e32 v55, v55, v57, vcc
	v_cndmask_b32_e32 v58, v58, v60, vcc
	v_cndmask_b32_e32 v59, v59, v61, vcc
	v_cndmask_b32_e32 v69, v69, v67, vcc
	v_cndmask_b32_e32 v68, v68, v66, vcc
	v_cndmask_b32_e32 v65, v65, v63, vcc
	v_cndmask_b32_e32 v64, v64, v62, vcc
	v_cmp_ne_u32_e32 vcc, 0, v50
	s_sub_i32 s15, s12, s13
	s_add_i32 s15, s15, -16
	s_cmp_eq_u32 s90, 0
	s_cselect_b32 s15, s13, s15
	s_cselect_b32 s14, 0, 15
	v_and_b32_e32 v50, 4, v168
	v_xor_b32_e32 v52, s14, v51
	v_cndmask_b32_e32 v54, v54, v58, vcc
	v_cndmask_b32_e32 v55, v55, v59, vcc
	v_cndmask_b32_e32 v69, v69, v65, vcc
	v_cndmask_b32_e32 v68, v68, v64, vcc
	v_cmp_ne_u32_e32 vcc, 0, v50
	s_ashr_i32 s12, s92, 6
	s_lshl_b32 s13, s12, 10
	s_add_i32 s68, s13, 0x2000
	s_lshl_b32 s69, s12, 8
	s_and_b64 s[12:13], s[80:81], exec
	s_cselect_b32 s68, s69, s68
	s_add_i32 s15, s68, s15
	v_lshlrev_b32_e32 v52, 12, v52
	v_lshl_add_u32 v52, v72, 1, v52
	v_cndmask_b32_e32 v54, v54, v69, vcc
	v_cndmask_b32_e32 v55, v55, v68, vcc
	s_mul_i32 s16, s90, 0x3000000
	s_lshl_b32 s17, s93, 7
	s_add_i32 s16, s16, s17
	s_lshl_b32 s17, s4, 1
	s_add_i32 s16, s16, s17
	s_lshl_b32 s17, s15, 12
	s_add_i32 s16, s16, s17
	s_add_u32 s10, s5, s16
	s_addc_u32 s11, s42, 0
	v_xor_b32_e32 v53, 0x1000, v52
	s_mov_b64 s[8:9], exec
	global_store_dword v52, v54, s[10:11]
	global_store_dword v53, v55, s[10:11]
